# plus chunk-scan instruction trimming (redundant SGPR reloads removed, o-tile LDS stores via one base + immediates)
# speedup vs baseline: 1.0323x; 1.0038x over previous
; #define LAS __attribute__((address_space(3)))
; template <class RecFn>
; __device__ __forceinline__ void gdn_scan(LAS unsigned char* lds, int bh, int b0, RecFn rec_of, const float* gtarr, bf16_t* zb, const float* gnorm_w, float* Sout, const unsigned* late_cnt, unsigned late_need, int cwait) {
;     ...
;         LAS unsigned char* buf = lds + P3_BUF + (c & 1) * REC_DMA;
;         u32x2 Uc[4];
; #pragma unroll
;         for (int rt = 0; rt < 4; ++rt) Uc[rt] = Un[rt];
;         const float gt = gtn;
;         const u32x4 zf0 = zp0, zf1 = zp1;
;         zp0 = zn0; zp1 = zn1;
;         if (c + 1 < NCHUNK) {
;             const unsigned char* rec = rec_of((bl * NCHUNK + c + 1) * 8 + h); LAS unsigned char* nb = lds + P3_BUF + ((c + 1) & 1) * REC_DMA;
; #pragma unroll
;             for (int pz = 0; pz < 7; ++pz) { const int piece = wave + 8 * pz; __builtin_amdgcn_global_load_lds((const unsigned*)(rec + piece * 1024 + lane * 16), (LAS unsigned*)(nb + piece * 1024), 16, 0, 0); }
; #pragma unroll
;             for (int rt = 0; rt < 4; ++rt) Un[rt] = *(const u32x2*)(rec + REC_U + ((rt * 8 + wave) * 64 + lane) * 8);
;             gtn = gtarr[(bl * NCHUNK + c + 1) * 8 + h];
;             { const int t = 64 * (c + 1) - 48 + zi; const bf16_t* zr = zb + (size_t)(b * LP + t) * D + h * 128 + 16 * zseg; zn0 = *(const u32x4*)zr; zn1 = *(const u32x4*)(zr + 8); }
;         }
.LBB0_780:
	v_mov_b64_e32 v[46:47], v[38:39]
	v_mov_b64_e32 v[50:51], v[42:43]
	s_cmp_eq_u32 s31, 32
	v_mov_b64_e32 v[88:89], v[86:87]
	v_mov_b64_e32 v[90:91], v[84:85]
	v_mov_b64_e32 v[92:93], v[82:83]
	v_mov_b64_e32 v[94:95], v[80:81]
	v_mov_b64_e32 v[44:45], v[36:37]
	v_mov_b64_e32 v[48:49], v[40:41]
	v_mov_b32_e32 v34, v76
	s_cbranch_scc1 .LBB0_782
	s_add_i32 s22, s31, s17
	s_lshl_b32 s22, s22, 3
	s_add_i32 s22, s22, s28
	s_add_i32 s24, s22, 0xfffff9c8
	s_ashr_i32 s23, s22, 31
	s_cmpk_lt_i32 s22, 0x638
	s_cselect_b32 s24, s22, s24
	s_cselect_b32 s25, s23, 0
	v_readlane_b32 s36, v245, 19
	v_readlane_b32 s48, v245, 31
	v_readlane_b32 s49, v245, 32
	s_mul_i32 s25, s25, 0x12000
	s_mul_hi_u32 s36, s24, 0x12000
	s_cselect_b32 s34, s64, s49
	s_cselect_b32 s35, s33, s48
	s_add_i32 s36, s36, s25
	s_mul_i32 s24, s24, 0x12000
	s_add_u32 s24, s35, s24
	s_addc_u32 s25, s34, s36
	s_bitcmp1_b32 s30, 0
	s_cselect_b32 s34, 0xe000, 0
	v_lshl_add_u64 v[44:45], s[24:25], 0, v[60:61]
	s_add_i32 s34, s26, s34
	v_lshl_add_u64 v[46:47], v[44:45], 0, s[0:1]
	s_mov_b32 m0, s34
	global_load_lds_dwordx4 v[46:47], off
	v_lshl_add_u64 v[46:47], v[44:45], 0, s[4:5]
	s_add_i32 m0, s34, 0x2000
	global_load_lds_dwordx4 v[46:47], off
	v_lshl_add_u64 v[46:47], v[44:45], 0, s[6:7]
	s_add_i32 m0, s34, 0x4000
	global_load_lds_dwordx4 v[46:47], off
	v_lshl_add_u64 v[46:47], v[44:45], 0, s[8:9]
	s_add_i32 m0, s34, 0x6000
	global_load_lds_dwordx4 v[46:47], off
	v_lshl_add_u64 v[46:47], v[44:45], 0, s[12:13]
	s_add_i32 m0, s34, 0x8000
	global_load_lds_dwordx4 v[46:47], off
	v_lshl_add_u64 v[46:47], v[44:45], 0, s[18:19]
	s_add_i32 m0, s34, 0xa000
	v_lshl_add_u64 v[44:45], v[44:45], 0, s[20:21]
	global_load_lds_dwordx4 v[46:47], off
	s_add_i32 m0, s34, 0xc000
	s_add_u32 s24, s24, 0xe000
	s_addc_u32 s25, s25, 0
	global_load_lds_dwordx4 v[44:45], off
	v_lshl_add_u64 v[44:45], s[24:25], 0, v[66:67]
	v_lshl_add_u64 v[46:47], s[24:25], 0, v[68:69]
	v_lshl_add_u64 v[48:49], s[24:25], 0, v[70:71]
	v_lshl_add_u64 v[50:51], s[24:25], 0, v[72:73]
	global_load_dwordx2 v[88:89], v[44:45], off
	global_load_dwordx2 v[90:91], v[46:47], off
	global_load_dwordx2 v[92:93], v[48:49], off
	global_load_dwordx2 v[94:95], v[50:51], off
	v_lshl_add_u32 v44, s30, 6, v114
	s_lshl_b64 s[22:23], s[22:23], 2
	v_ashrrev_i32_e32 v45, 31, v44
	s_add_u32 s22, s58, s22
	v_lshlrev_b64 v[44:45], 11, v[44:45]
	s_addc_u32 s23, s57, s23
	v_lshl_add_u64 v[48:49], v[74:75], 0, v[44:45]
	global_load_dword v34, v35, s[22:23]
	global_load_dwordx4 v[44:47], v[48:49], off offset:16
	s_nop 0
	global_load_dwordx4 v[48:51], v[48:49], off

; #define MFMA16(a, b, c) __builtin_amdgcn_mfma_f32_16x16x32_bf16(a, b, c, 0, 0, 0)
; #define PIN8(f) asm volatile("" : "+v"(f[0]), "+v"(f[1]), "+v"(f[2]), "+v"(f[3]), "+v"(f[4]), "+v"(f[5]), "+v"(f[6]), "+v"(f[7])); __builtin_amdgcn_sched_barrier(0)
; template <class RecFn>
; __device__ __forceinline__ void gdn_scan(LAS unsigned char* lds, int bh, int b0, RecFn rec_of, const float* gtarr, bf16_t* zb, const float* gnorm_w, float* Sout, const unsigned* late_cnt, unsigned late_need, int cwait) {
;     ...
;         bf16x8 Sb[4];
; #pragma unroll
;         for (int s2 = 0; s2 < 4; ++s2) Sb[s2] = pack8(S[2 * s2], S[2 * s2 + 1]);
;     ...
;         f32x4 av[4], ao[4];
;         bf16x8 fa[8], fb[8];
; #pragma unroll
;         for (int s2 = 0; s2 < 4; ++s2) { fa[s2] = LDF(REC_WN + (0 * 4 + s2) * 1024); fa[4 + s2] = LDF(REC_QD + (0 * 4 + s2) * 1024); }
; #pragma unroll
;         for (int rt = 0; rt < 4; ++rt) {
;             av[rt] = (f32x4){__uint_as_float(Uc[rt].x << 16), __uint_as_float(Uc[rt].x & 0xffff0000u), __uint_as_float(Uc[rt].y << 16), __uint_as_float(Uc[rt].y & 0xffff0000u)};
;             ao[rt] = z4;
;             bf16x8 (&cur)[8] = (rt & 1) ? fb : fa; bf16x8 (&nxt)[8] = (rt & 1) ? fa : fb;
;             if (rt < 3) {
; #pragma unroll
;                 for (int s2 = 0; s2 < 4; ++s2) { nxt[s2] = LDF(REC_WN + ((rt + 1) * 4 + s2) * 1024); nxt[4 + s2] = LDF(REC_QD + ((rt + 1) * 4 + s2) * 1024); }
;             } else {
; #pragma unroll
;                 for (int q = 0; q < 8; ++q) nxt[q] = LDF(REC_AM + q * 1024);
;             }
;             PIN8(cur);
; #pragma unroll
;             for (int s2 = 0; s2 < 4; ++s2) { av[rt] = MFMA16(cur[s2], Sb[s2], av[rt]); ao[rt] = MFMA16(cur[4 + s2], Sb[s2], ao[rt]); }
;             __builtin_amdgcn_sched_barrier(0);
;         }
;         bf16x8 Vb[2];
; #pragma unroll
;         for (int s = 0; s < 2; ++s) Vb[s] = pack8(av[2 * s], av[2 * s + 1]);
.LBB0_786:
	s_and_b32 s22, s31, 1
	s_mul_i32 s23, s22, 0xe000
	v_add_u32_e32 v214, s23, v132
	ds_read_b128 v[108:111], v214 offset:19456
	ds_read_b128 v[134:137], v214 offset:18432
	ds_read_b128 v[138:141], v214 offset:3072
	ds_read_b128 v[142:145], v214 offset:2048
	ds_read_b128 v[146:149], v214 offset:17408
	ds_read_b128 v[150:153], v214 offset:16384
	ds_read_b128 v[154:157], v214 offset:1024
	ds_read_b128 v[158:161], v214
	ds_read_b128 v[162:165], v214 offset:23552
	ds_read_b128 v[166:169], v214 offset:22528
	ds_read_b128 v[170:173], v214 offset:7168
	ds_read_b128 v[174:177], v214 offset:6144
	ds_read_b128 v[178:181], v214 offset:21504
	ds_read_b128 v[182:185], v214 offset:20480
	ds_read_b128 v[186:189], v214 offset:5120
	ds_read_b128 v[190:193], v214 offset:4096
	v_cvt_pk_bf16_f32 v52, v30, v31
	v_cvt_pk_bf16_f32 v53, v32, v33
	v_cvt_pk_bf16_f32 v54, v26, v27
	v_cvt_pk_bf16_f32 v55, v28, v29
	v_cvt_pk_bf16_f32 v56, v22, v23
	v_cvt_pk_bf16_f32 v57, v24, v25
	v_cvt_pk_bf16_f32 v58, v2, v3
	v_cvt_pk_bf16_f32 v59, v4, v5
	v_cvt_pk_bf16_f32 v96, v10, v11
	v_cvt_pk_bf16_f32 v97, v12, v13
	v_cvt_pk_bf16_f32 v98, v18, v19
	v_cvt_pk_bf16_f32 v99, v20, v21
	v_cvt_pk_bf16_f32 v100, v14, v15
	v_cvt_pk_bf16_f32 v101, v16, v17
	v_cvt_pk_bf16_f32 v102, v6, v7
	v_cvt_pk_bf16_f32 v103, v8, v9
	v_lshlrev_b32_e32 v104, 16, v86
	v_and_b32_e32 v105, 0xffff0000, v86
	v_lshlrev_b32_e32 v106, 16, v87
	v_and_b32_e32 v107, 0xffff0000, v87
	s_waitcnt lgkmcnt(0)
	s_nop 0
	v_mfma_f32_16x16x32_bf16 v[104:107], v[158:161], v[52:55], v[104:107]
	v_mfma_f32_16x16x32_bf16 v[150:153], v[150:153], v[52:55], 0
	v_mfma_f32_16x16x32_bf16 v[104:107], v[154:157], v[56:59], v[104:107]
	v_mfma_f32_16x16x32_bf16 v[146:149], v[146:149], v[56:59], v[150:153]
	v_mfma_f32_16x16x32_bf16 v[104:107], v[142:145], v[96:99], v[104:107]
	v_mfma_f32_16x16x32_bf16 v[134:137], v[134:137], v[96:99], v[146:149]
	v_mfma_f32_16x16x32_bf16 v[104:107], v[138:141], v[100:103], v[104:107]
	v_mfma_f32_16x16x32_bf16 v[108:111], v[108:111], v[100:103], v[134:137]
	ds_read_b128 v[138:141], v214 offset:27648
	ds_read_b128 v[142:145], v214 offset:26624
	s_nop 1
	ds_read_b128 v[146:149], v214 offset:11264
	ds_read_b128 v[150:153], v214 offset:10240
	ds_read_b128 v[154:157], v214 offset:25600
	ds_read_b128 v[158:161], v214 offset:24576
	ds_read_b128 v[194:197], v214 offset:9216
	ds_read_b128 v[198:201], v214 offset:8192
	v_lshlrev_b32_e32 v134, 16, v84
	v_and_b32_e32 v135, 0xffff0000, v84
	v_lshlrev_b32_e32 v136, 16, v85
	v_and_b32_e32 v137, 0xffff0000, v85
	s_nop 1
	v_mfma_f32_16x16x32_bf16 v[84:87], v[190:193], v[52:55], v[134:137]
	v_mfma_f32_16x16x32_bf16 v[134:137], v[182:185], v[52:55], 0
	v_mfma_f32_16x16x32_bf16 v[84:87], v[186:189], v[56:59], v[84:87]
	v_mfma_f32_16x16x32_bf16 v[134:137], v[178:181], v[56:59], v[134:137]
	v_mfma_f32_16x16x32_bf16 v[84:87], v[174:177], v[96:99], v[84:87]
	v_mfma_f32_16x16x32_bf16 v[134:137], v[166:169], v[96:99], v[134:137]
	v_mfma_f32_16x16x32_bf16 v[84:87], v[170:173], v[100:103], v[84:87]
	v_mfma_f32_16x16x32_bf16 v[134:137], v[162:165], v[100:103], v[134:137]
	ds_read_b128 v[166:169], v214 offset:31744
	ds_read_b128 v[170:173], v214 offset:30720
	ds_read_b128 v[174:177], v214 offset:15360
	ds_read_b128 v[178:181], v214 offset:14336
	ds_read_b128 v[182:185], v214 offset:29696
	ds_read_b128 v[186:189], v214 offset:28672
	ds_read_b128 v[190:193], v214 offset:13312
	ds_read_b128 v[202:205], v214 offset:12288
	v_lshlrev_b32_e32 v162, 16, v82
	v_and_b32_e32 v163, 0xffff0000, v82
	v_lshlrev_b32_e32 v164, 16, v83
	v_and_b32_e32 v165, 0xffff0000, v83
	s_waitcnt lgkmcnt(0)
	s_nop 0
	v_mfma_f32_16x16x32_bf16 v[162:165], v[198:201], v[52:55], v[162:165]
	v_mfma_f32_16x16x32_bf16 v[158:161], v[158:161], v[52:55], 0
	v_mfma_f32_16x16x32_bf16 v[162:165], v[194:197], v[56:59], v[162:165]
	v_mfma_f32_16x16x32_bf16 v[154:157], v[154:157], v[56:59], v[158:161]
	v_mfma_f32_16x16x32_bf16 v[150:153], v[150:153], v[96:99], v[162:165]
	v_mfma_f32_16x16x32_bf16 v[142:145], v[142:145], v[96:99], v[154:157]
	v_mfma_f32_16x16x32_bf16 v[146:149], v[146:149], v[100:103], v[150:153]
	v_mfma_f32_16x16x32_bf16 v[138:141], v[138:141], v[100:103], v[142:145]
	s_nop 4
	ds_read_b128 v[150:153], v214 offset:49152
	ds_read_b128 v[154:157], v214 offset:50176
	ds_read_b128 v[158:161], v214 offset:51200
	ds_read_b128 v[162:165], v214 offset:52224
	ds_read_b128 v[194:197], v214 offset:53248
	ds_read_b128 v[198:201], v214 offset:54272
	ds_read_b128 v[206:209], v214 offset:55296
	ds_read_b128 v[210:213], v214 offset:56320
	v_lshlrev_b32_e32 v142, 16, v80
	v_and_b32_e32 v143, 0xffff0000, v80
	v_lshlrev_b32_e32 v144, 16, v81
	v_and_b32_e32 v145, 0xffff0000, v81
	s_nop 1
	v_mfma_f32_16x16x32_bf16 v[80:83], v[202:205], v[52:55], v[142:145]
	v_mfma_f32_16x16x32_bf16 v[52:55], v[186:189], v[52:55], 0
	v_mfma_f32_16x16x32_bf16 v[80:83], v[190:193], v[56:59], v[80:83]
	v_mfma_f32_16x16x32_bf16 v[52:55], v[182:185], v[56:59], v[52:55]
	v_mfma_f32_16x16x32_bf16 v[56:59], v[178:181], v[96:99], v[80:83]
	v_mfma_f32_16x16x32_bf16 v[52:55], v[170:173], v[96:99], v[52:55]
	v_mfma_f32_16x16x32_bf16 v[56:59], v[174:177], v[100:103], v[56:59]
	v_mfma_f32_16x16x32_bf16 v[52:55], v[166:169], v[100:103], v[52:55]
	s_nop 2
	v_cvt_pk_bf16_f32 v80, v104, v105
	v_cvt_pk_bf16_f32 v81, v106, v107
	ds_read_b128 v[96:99], v214 offset:39936
	ds_read_b128 v[100:103], v214 offset:38912
	ds_read_b128 v[104:107], v214 offset:37888
	ds_read_b128 v[142:145], v214 offset:36864
	ds_read_b128 v[166:169], v214 offset:35840
	ds_read_b128 v[170:173], v214 offset:34816
	ds_read_b128 v[174:177], v214 offset:33792
	ds_read_b128 v[178:181], v214 offset:32768
	v_cvt_pk_bf16_f32 v82, v84, v85
	v_cvt_pk_bf16_f32 v83, v86, v87
	v_cvt_pk_bf16_f32 v84, v146, v147
	v_cvt_pk_bf16_f32 v85, v148, v149
	v_cvt_pk_bf16_f32 v86, v56, v57
	v_cvt_pk_bf16_f32 v87, v58, v59
	s_waitcnt lgkmcnt(0)
; #define LAS __attribute__((address_space(3)))
; __device__ __forceinline__ unsigned cvt_pk_bf16(float lo, float hi) { const bf16x2_t r = __builtin_convertvector((f32x2){lo, hi}, bf16x2_t); return __builtin_bit_cast(unsigned, r); }
; #define MFMA16(a, b, c) __builtin_amdgcn_mfma_f32_16x16x32_bf16(a, b, c, 0, 0, 0)
; #define PIN8(f) asm volatile("" : "+v"(f[0]), "+v"(f[1]), "+v"(f[2]), "+v"(f[3]), "+v"(f[4]), "+v"(f[5]), "+v"(f[6]), "+v"(f[7])); __builtin_amdgcn_sched_barrier(0)
; template <class RecFn>
; __device__ __forceinline__ void gdn_scan(LAS unsigned char* lds, int bh, int b0, RecFn rec_of, const float* gtarr, bf16_t* zb, const float* gnorm_w, float* Sout, const unsigned* late_cnt, unsigned late_need, int cwait) {
;     ...
; #pragma unroll
;         for (int q = 0; q < 8; ++q) fb[q] = LDF(REC_KDT + q * 1024);
;         PIN8(fa);
; #pragma unroll
;         for (int rt = 0; rt < 4; ++rt)
; #pragma unroll
;             for (int s = 0; s < 2; ++s) ao[rt] = MFMA16(fa[rt * 2 + s], Vb[s], ao[rt]);
;         __builtin_amdgcn_sched_barrier(0);
; #pragma unroll
;         for (int q = 0; q < 8; ++q) fa[q] = LDF(REC_KDT + (8 + q) * 1024);
;         PIN8(fb);
; #pragma unroll
;         for (int dt = 0; dt < 4; ++dt) { S[dt] = S[dt] * gt;
; #pragma unroll
;             for (int s = 0; s < 2; ++s) S[dt] = MFMA16(fb[dt * 2 + s], Vb[s], S[dt]); }
;         __builtin_amdgcn_sched_barrier(0);
;         PIN8(fa);
; #pragma unroll
;         for (int dt = 4; dt < 8; ++dt) { S[dt] = S[dt] * gt;
; #pragma unroll
;             for (int s = 0; s < 2; ++s) S[dt] = MFMA16(fa[(dt - 4) * 2 + s], Vb[s], S[dt]); }
;     ...
;         { LAS unsigned char* ost = lds + P3_OST + (c & 1) * P3_OSTB;
; #pragma unroll
;           for (int rt = 0; rt < 4; ++rt)
; #pragma unroll
;             for (int r = 0; r < 4; ++r) { const int i = 16 * rt + 4 * g + r; const float v = ao[rt][r];
;                 *(LAS bf16_t*)(ost + (i * 132 + 16 * wave + l15) * 2) = (bf16_t)(cvt_pk_bf16(v, 0.f) & 0xffffu); } }
;         asm volatile("s_waitcnt vmcnt(0)" ::: "memory");
;         __syncthreads();
	s_nop 0
	v_mfma_f32_16x16x32_bf16 v[56:59], v[150:153], v[80:83], v[108:111]
	v_mfma_f32_16x16x32_bf16 v[108:111], v[158:161], v[80:83], v[134:137]
	v_mfma_f32_16x16x32_bf16 v[134:137], v[194:197], v[80:83], v[138:141]
	v_mfma_f32_16x16x32_bf16 v[52:55], v[206:209], v[80:83], v[52:55]
	v_mfma_f32_16x16x32_bf16 v[56:59], v[154:157], v[84:87], v[56:59]
	v_mfma_f32_16x16x32_bf16 v[108:111], v[162:165], v[84:87], v[108:111]
	v_mfma_f32_16x16x32_bf16 v[134:137], v[198:201], v[84:87], v[134:137]
	v_mfma_f32_16x16x32_bf16 v[52:55], v[210:213], v[84:87], v[52:55]
	ds_read_b128 v[138:141], v214 offset:48128
	ds_read_b128 v[146:149], v214 offset:47104
	ds_read_b128 v[150:153], v214 offset:46080
	ds_read_b128 v[154:157], v214 offset:45056
	ds_read_b128 v[158:161], v214 offset:44032
	ds_read_b128 v[162:165], v214 offset:43008
	ds_read_b128 v[182:185], v214 offset:41984
	ds_read_b128 v[186:189], v214 offset:40960
	v_pk_mul_f32 v[32:33], v[76:77], v[32:33] op_sel_hi:[0,1]
	v_pk_mul_f32 v[30:31], v[76:77], v[30:31] op_sel_hi:[0,1]
	v_pk_mul_f32 v[28:29], v[76:77], v[28:29] op_sel_hi:[0,1]
	v_pk_mul_f32 v[26:27], v[76:77], v[26:27] op_sel_hi:[0,1]
	v_pk_mul_f32 v[24:25], v[76:77], v[24:25] op_sel_hi:[0,1]
	v_pk_mul_f32 v[22:23], v[76:77], v[22:23] op_sel_hi:[0,1]
	v_pk_mul_f32 v[4:5], v[76:77], v[4:5] op_sel_hi:[0,1]
	v_pk_mul_f32 v[2:3], v[76:77], v[2:3] op_sel_hi:[0,1]
	v_mfma_f32_16x16x32_bf16 v[30:33], v[178:181], v[80:83], v[30:33]
	v_mfma_f32_16x16x32_bf16 v[26:29], v[170:173], v[80:83], v[26:29]
	v_mfma_f32_16x16x32_bf16 v[22:25], v[142:145], v[80:83], v[22:25]
	v_mfma_f32_16x16x32_bf16 v[2:5], v[100:103], v[80:83], v[2:5]
	v_mfma_f32_16x16x32_bf16 v[30:33], v[174:177], v[84:87], v[30:33]
	v_mfma_f32_16x16x32_bf16 v[26:29], v[166:169], v[84:87], v[26:29]
	v_mfma_f32_16x16x32_bf16 v[22:25], v[104:107], v[84:87], v[22:25]
	v_mfma_f32_16x16x32_bf16 v[2:5], v[96:99], v[84:87], v[2:5]
	s_waitcnt lgkmcnt(0)
	s_mulk_i32 s22, 0x4200
	s_add_i32 s22, s22, 0
	s_add_i32 s22, s22, 0x1c000
	v_pk_mul_f32 v[12:13], v[76:77], v[12:13] op_sel_hi:[0,1]
	v_pk_mul_f32 v[10:11], v[76:77], v[10:11] op_sel_hi:[0,1]
	v_pk_mul_f32 v[20:21], v[76:77], v[20:21] op_sel_hi:[0,1]
	v_pk_mul_f32 v[18:19], v[76:77], v[18:19] op_sel_hi:[0,1]
	v_pk_mul_f32 v[16:17], v[76:77], v[16:17] op_sel_hi:[0,1]
	v_pk_mul_f32 v[14:15], v[76:77], v[14:15] op_sel_hi:[0,1]
	v_pk_mul_f32 v[8:9], v[76:77], v[8:9] op_sel_hi:[0,1]
	v_pk_mul_f32 v[6:7], v[76:77], v[6:7] op_sel_hi:[0,1]
	v_cvt_pk_bf16_f32 v56, v56, s0
	v_add_u32_e32 v76, s22, v116
	ds_write_b16 v76, v56
	v_cvt_pk_bf16_f32 v56, v57, s0
	ds_write_b16 v76, v56 offset:264
	v_cvt_pk_bf16_f32 v56, v58, s0
	ds_write_b16 v76, v56 offset:528
	v_cvt_pk_bf16_f32 v56, v59, s0
	ds_write_b16 v76, v56 offset:792
	v_cvt_pk_bf16_f32 v56, v108, s0
	ds_write_b16 v76, v56 offset:4224
	v_cvt_pk_bf16_f32 v56, v109, s0
	ds_write_b16 v76, v56 offset:4488
	v_cvt_pk_bf16_f32 v56, v110, s0
	ds_write_b16 v76, v56 offset:4752
	v_cvt_pk_bf16_f32 v56, v111, s0
	ds_write_b16 v76, v56 offset:5016
	v_cvt_pk_bf16_f32 v56, v134, s0
	ds_write_b16 v76, v56 offset:8448
	v_cvt_pk_bf16_f32 v56, v135, s0
	ds_write_b16 v76, v56 offset:8712
	v_cvt_pk_bf16_f32 v56, v136, s0
	ds_write_b16 v76, v56 offset:8976
	v_cvt_pk_bf16_f32 v56, v137, s0
	v_mfma_f32_16x16x32_bf16 v[10:13], v[186:189], v[80:83], v[10:13]
	ds_write_b16 v76, v56 offset:9240
	v_cvt_pk_bf16_f32 v52, v52, s0
	v_mfma_f32_16x16x32_bf16 v[18:21], v[162:165], v[80:83], v[18:21]
	ds_write_b16 v76, v52 offset:12672
	v_cvt_pk_bf16_f32 v52, v53, s0
	v_mfma_f32_16x16x32_bf16 v[14:17], v[154:157], v[80:83], v[14:17]
	ds_write_b16 v76, v52 offset:12936
	v_cvt_pk_bf16_f32 v52, v54, s0
	v_mfma_f32_16x16x32_bf16 v[6:9], v[146:149], v[80:83], v[6:9]
	ds_write_b16 v76, v52 offset:13200
	v_cvt_pk_bf16_f32 v52, v55, s0
	v_mfma_f32_16x16x32_bf16 v[10:13], v[182:185], v[84:87], v[10:13]
	ds_write_b16 v76, v52 offset:13464
	s_waitcnt vmcnt(0)
	s_cmp_eq_u32 s30, 33
	v_mfma_f32_16x16x32_bf16 v[18:21], v[158:161], v[84:87], v[18:21]
	s_waitcnt vmcnt(0) lgkmcnt(0)
	s_barrier
	v_mfma_f32_16x16x32_bf16 v[14:17], v[150:153], v[84:87], v[14:17]
	v_mfma_f32_16x16x32_bf16 v[6:9], v[138:141], v[84:87], v[6:9]
	s_cbranch_scc1 .LBB0_788
	v_mov_b64_e32 v[58:59], v[42:43]
	v_mov_b64_e32 v[54:55], v[38:39]
	v_mov_b64_e32 v[86:87], v[88:89]
	v_mov_b64_e32 v[84:85], v[90:91]
	v_mov_b64_e32 v[82:83], v[92:93]
	v_mov_b64_e32 v[80:81], v[94:95]
	v_mov_b32_e32 v76, v34
	v_mov_b64_e32 v[56:57], v[40:41]
	v_mov_b64_e32 v[52:53], v[36:37]
	s_mov_b32 s31, s30
	s_branch .LBB0_763
